# streaming final stores: v92 with sc1 nt on the final output stores (never re-read on the device)
# speedup vs baseline: 1.0041x; 1.0041x over previous
.Lfz_bar_end_a:
	s_or_b64 exec, exec, s[0:1]
	s_barrier
	v_lshrrev_b32_e32 v232, 12, v228
	v_lshlrev_b32_e32 v232, 4, v232
	v_add_u32_e32 v233, 0x0, v232
	v_add_u32_e32 v234, 0x100, v232
	v_add_u32_e32 v235, 0x200, v232
	v_add_u32_e32 v236, 0x300, v232
	v_add_u32_e32 v237, 0x800, v232
	v_add_u32_e32 v238, 0x900, v232
	v_add_u32_e32 v239, 0xa00, v232
	v_add_u32_e32 v240, 0xb00, v232
	global_load_dwordx4 v[180:183], v233, s[50:51]
	global_load_dwordx4 v[184:187], v234, s[50:51]
	global_load_dwordx4 v[188:191], v235, s[50:51]
	global_load_dwordx4 v[192:195], v236, s[50:51]
	global_load_dwordx4 v[196:199], v237, s[50:51]
	global_load_dwordx4 v[200:203], v238, s[50:51]
	global_load_dwordx4 v[204:207], v239, s[50:51]
	global_load_dwordx4 v[208:211], v240, s[50:51]
	s_waitcnt vmcnt(0)
	v_mov_b32_e32 v242, 0x3a800000
	v_mov_b32_e32 v243, 0x358637bd
	v_add_f32_e32 v160, v180, v181
	v_add_f32_e32 v160, v160, v182
	v_add_f32_e32 v160, v160, v183
	v_fma_f32 v160, v160, v242, v243
	v_add_f32_e32 v161, v184, v185
	v_add_f32_e32 v161, v161, v186
	v_add_f32_e32 v161, v161, v187
	v_fma_f32 v161, v161, v242, v243
	v_add_f32_e32 v162, v188, v189
	v_add_f32_e32 v162, v162, v190
	v_add_f32_e32 v162, v162, v191
	v_fma_f32 v162, v162, v242, v243
	v_add_f32_e32 v163, v192, v193
	v_add_f32_e32 v163, v163, v194
	v_add_f32_e32 v163, v163, v195
	v_fma_f32 v163, v163, v242, v243
	v_add_f32_e32 v164, v196, v197
	v_add_f32_e32 v164, v164, v198
	v_add_f32_e32 v164, v164, v199
	v_fma_f32 v164, v164, v242, v243
	v_add_f32_e32 v165, v200, v201
	v_add_f32_e32 v165, v165, v202
	v_add_f32_e32 v165, v165, v203
	v_fma_f32 v165, v165, v242, v243
	v_add_f32_e32 v166, v204, v205
	v_add_f32_e32 v166, v166, v206
	v_add_f32_e32 v166, v166, v207
	v_fma_f32 v166, v166, v242, v243
	v_add_f32_e32 v167, v208, v209
	v_add_f32_e32 v167, v167, v210
	v_add_f32_e32 v167, v167, v211
	v_fma_f32 v167, v167, v242, v243
	v_rsq_f32_e32 v160, v160
	v_rsq_f32_e32 v161, v161
	v_rsq_f32_e32 v162, v162
	v_rsq_f32_e32 v163, v163
	v_rsq_f32_e32 v164, v164
	v_rsq_f32_e32 v165, v165
	v_rsq_f32_e32 v166, v166
	v_rsq_f32_e32 v167, v167
	s_nop 0
	s_add_u32 s48, s42, 0x0
	s_addc_u32 s49, s43, 0
	v_mul_f32_e32 v140, v140, v160
	v_mul_f32_e32 v141, v141, v160
	v_mul_f32_e32 v142, v142, v160
	v_mul_f32_e32 v143, v143, v160
	v_pk_mul_f32 v[140:141], v[140:141], v[212:213]
	v_pk_mul_f32 v[142:143], v[142:143], v[214:215]
	v_mul_f32_e32 v136, v136, v160
	v_mul_f32_e32 v137, v137, v160
	v_mul_f32_e32 v138, v138, v160
	v_mul_f32_e32 v139, v139, v160
	v_pk_mul_f32 v[136:137], v[136:137], v[216:217]
	v_pk_mul_f32 v[138:139], v[138:139], v[218:219]
	v_mul_f32_e32 v132, v132, v160
	v_mul_f32_e32 v133, v133, v160
	v_mul_f32_e32 v134, v134, v160
	v_mul_f32_e32 v135, v135, v160
	v_pk_mul_f32 v[132:133], v[132:133], v[220:221]
	v_pk_mul_f32 v[134:135], v[134:135], v[222:223]
	v_mul_f32_e32 v128, v128, v160
	v_mul_f32_e32 v129, v129, v160
	v_mul_f32_e32 v130, v130, v160
	v_mul_f32_e32 v131, v131, v160
	v_pk_mul_f32 v[128:129], v[128:129], v[224:225]
	v_pk_mul_f32 v[130:131], v[130:131], v[226:227]
	global_store_dwordx4 v228, v[140:143], s[48:49] sc1 nt
	global_store_dwordx4 v228, v[136:139], s[48:49] offset:64 sc1 nt
	global_store_dwordx4 v228, v[132:135], s[48:49] offset:512 sc1 nt
	global_store_dwordx4 v228, v[128:131], s[48:49] offset:576 sc1 nt
	s_add_u32 s48, s42, 0x10000
	s_addc_u32 s49, s43, 0
	v_mul_f32_e32 v124, v124, v161
	v_mul_f32_e32 v125, v125, v161
	v_mul_f32_e32 v126, v126, v161
	v_mul_f32_e32 v127, v127, v161
	v_pk_mul_f32 v[124:125], v[124:125], v[212:213]
	v_pk_mul_f32 v[126:127], v[126:127], v[214:215]
	v_mul_f32_e32 v120, v120, v161
	v_mul_f32_e32 v121, v121, v161
	v_mul_f32_e32 v122, v122, v161
	v_mul_f32_e32 v123, v123, v161
	v_pk_mul_f32 v[120:121], v[120:121], v[216:217]
	v_pk_mul_f32 v[122:123], v[122:123], v[218:219]
	v_mul_f32_e32 v116, v116, v161
	v_mul_f32_e32 v117, v117, v161
	v_mul_f32_e32 v118, v118, v161
	v_mul_f32_e32 v119, v119, v161
	v_pk_mul_f32 v[116:117], v[116:117], v[220:221]
	v_pk_mul_f32 v[118:119], v[118:119], v[222:223]
	v_mul_f32_e32 v112, v112, v161
	v_mul_f32_e32 v113, v113, v161
	v_mul_f32_e32 v114, v114, v161
	v_mul_f32_e32 v115, v115, v161
	v_pk_mul_f32 v[112:113], v[112:113], v[224:225]
	v_pk_mul_f32 v[114:115], v[114:115], v[226:227]
	global_store_dwordx4 v228, v[124:127], s[48:49] sc1 nt
	global_store_dwordx4 v228, v[120:123], s[48:49] offset:64 sc1 nt
	global_store_dwordx4 v228, v[116:119], s[48:49] offset:512 sc1 nt
	global_store_dwordx4 v228, v[112:115], s[48:49] offset:576 sc1 nt
	s_add_u32 s48, s42, 0x20000
	s_addc_u32 s49, s43, 0
	v_mul_f32_e32 v108, v108, v162
	v_mul_f32_e32 v109, v109, v162
	v_mul_f32_e32 v110, v110, v162
	v_mul_f32_e32 v111, v111, v162
	v_pk_mul_f32 v[108:109], v[108:109], v[212:213]
	v_pk_mul_f32 v[110:111], v[110:111], v[214:215]
	v_mul_f32_e32 v104, v104, v162
	v_mul_f32_e32 v105, v105, v162
	v_mul_f32_e32 v106, v106, v162
	v_mul_f32_e32 v107, v107, v162
	v_pk_mul_f32 v[104:105], v[104:105], v[216:217]
	v_pk_mul_f32 v[106:107], v[106:107], v[218:219]
	v_mul_f32_e32 v96, v96, v162
	v_mul_f32_e32 v97, v97, v162
	v_mul_f32_e32 v98, v98, v162
	v_mul_f32_e32 v99, v99, v162
	v_pk_mul_f32 v[96:97], v[96:97], v[220:221]
	v_pk_mul_f32 v[98:99], v[98:99], v[222:223]
	v_mul_f32_e32 v88, v88, v162
	v_mul_f32_e32 v89, v89, v162
	v_mul_f32_e32 v90, v90, v162
	v_mul_f32_e32 v91, v91, v162
	v_pk_mul_f32 v[88:89], v[88:89], v[224:225]
	v_pk_mul_f32 v[90:91], v[90:91], v[226:227]
	global_store_dwordx4 v228, v[108:111], s[48:49] sc1 nt
	global_store_dwordx4 v228, v[104:107], s[48:49] offset:64 sc1 nt
	global_store_dwordx4 v228, v[96:99], s[48:49] offset:512 sc1 nt
	global_store_dwordx4 v228, v[88:91], s[48:49] offset:576 sc1 nt
	s_add_u32 s48, s42, 0x30000
	s_addc_u32 s49, s43, 0
	v_mul_f32_e32 v76, v76, v163
	v_mul_f32_e32 v77, v77, v163
	v_mul_f32_e32 v78, v78, v163
	v_mul_f32_e32 v79, v79, v163
	v_pk_mul_f32 v[76:77], v[76:77], v[212:213]
	v_pk_mul_f32 v[78:79], v[78:79], v[214:215]
	v_mul_f32_e32 v72, v72, v163
	v_mul_f32_e32 v73, v73, v163
	v_mul_f32_e32 v74, v74, v163
	v_mul_f32_e32 v75, v75, v163
	v_pk_mul_f32 v[72:73], v[72:73], v[216:217]
	v_pk_mul_f32 v[74:75], v[74:75], v[218:219]
	v_mul_f32_e32 v68, v68, v163
	v_mul_f32_e32 v69, v69, v163
	v_mul_f32_e32 v70, v70, v163
	v_mul_f32_e32 v71, v71, v163
	v_pk_mul_f32 v[68:69], v[68:69], v[220:221]
	v_pk_mul_f32 v[70:71], v[70:71], v[222:223]
	v_mul_f32_e32 v64, v64, v163
	v_mul_f32_e32 v65, v65, v163
	v_mul_f32_e32 v66, v66, v163
	v_mul_f32_e32 v67, v67, v163
	v_pk_mul_f32 v[64:65], v[64:65], v[224:225]
	v_pk_mul_f32 v[66:67], v[66:67], v[226:227]
	global_store_dwordx4 v228, v[76:79], s[48:49] sc1 nt
	global_store_dwordx4 v228, v[72:75], s[48:49] offset:64 sc1 nt
	global_store_dwordx4 v228, v[68:71], s[48:49] offset:512 sc1 nt
	global_store_dwordx4 v228, v[64:67], s[48:49] offset:576 sc1 nt
	s_add_u32 s48, s42, 0x80000
	s_addc_u32 s49, s43, 0
	v_mul_f32_e32 v60, v60, v164
	v_mul_f32_e32 v61, v61, v164
	v_mul_f32_e32 v62, v62, v164
	v_mul_f32_e32 v63, v63, v164
	v_pk_mul_f32 v[60:61], v[60:61], v[212:213]
	v_pk_mul_f32 v[62:63], v[62:63], v[214:215]
	v_mul_f32_e32 v56, v56, v164
	v_mul_f32_e32 v57, v57, v164
	v_mul_f32_e32 v58, v58, v164
	v_mul_f32_e32 v59, v59, v164
	v_pk_mul_f32 v[56:57], v[56:57], v[216:217]
	v_pk_mul_f32 v[58:59], v[58:59], v[218:219]
	v_mul_f32_e32 v52, v52, v164
	v_mul_f32_e32 v53, v53, v164
	v_mul_f32_e32 v54, v54, v164
	v_mul_f32_e32 v55, v55, v164
	v_pk_mul_f32 v[52:53], v[52:53], v[220:221]
	v_pk_mul_f32 v[54:55], v[54:55], v[222:223]
	v_mul_f32_e32 v48, v48, v164
	v_mul_f32_e32 v49, v49, v164
	v_mul_f32_e32 v50, v50, v164
	v_mul_f32_e32 v51, v51, v164
	v_pk_mul_f32 v[48:49], v[48:49], v[224:225]
	v_pk_mul_f32 v[50:51], v[50:51], v[226:227]
	global_store_dwordx4 v228, v[60:63], s[48:49] sc1 nt
	global_store_dwordx4 v228, v[56:59], s[48:49] offset:64 sc1 nt
	global_store_dwordx4 v228, v[52:55], s[48:49] offset:512 sc1 nt
	global_store_dwordx4 v228, v[48:51], s[48:49] offset:576 sc1 nt
	s_add_u32 s48, s42, 0x90000
	s_addc_u32 s49, s43, 0
	v_mul_f32_e32 v44, v44, v165
	v_mul_f32_e32 v45, v45, v165
	v_mul_f32_e32 v46, v46, v165
	v_mul_f32_e32 v47, v47, v165
	v_pk_mul_f32 v[44:45], v[44:45], v[212:213]
	v_pk_mul_f32 v[46:47], v[46:47], v[214:215]
	v_mul_f32_e32 v40, v40, v165
	v_mul_f32_e32 v41, v41, v165
	v_mul_f32_e32 v42, v42, v165
	v_mul_f32_e32 v43, v43, v165
	v_pk_mul_f32 v[40:41], v[40:41], v[216:217]
	v_pk_mul_f32 v[42:43], v[42:43], v[218:219]
	v_mul_f32_e32 v36, v36, v165
	v_mul_f32_e32 v37, v37, v165
	v_mul_f32_e32 v38, v38, v165
	v_mul_f32_e32 v39, v39, v165
	v_pk_mul_f32 v[36:37], v[36:37], v[220:221]
	v_pk_mul_f32 v[38:39], v[38:39], v[222:223]
	v_mul_f32_e32 v32, v32, v165
	v_mul_f32_e32 v33, v33, v165
	v_mul_f32_e32 v34, v34, v165
	v_mul_f32_e32 v35, v35, v165
	v_pk_mul_f32 v[32:33], v[32:33], v[224:225]
	v_pk_mul_f32 v[34:35], v[34:35], v[226:227]
	global_store_dwordx4 v228, v[44:47], s[48:49] sc1 nt
	global_store_dwordx4 v228, v[40:43], s[48:49] offset:64 sc1 nt
	global_store_dwordx4 v228, v[36:39], s[48:49] offset:512 sc1 nt
	global_store_dwordx4 v228, v[32:35], s[48:49] offset:576 sc1 nt
	s_add_u32 s48, s42, 0xa0000
	s_addc_u32 s49, s43, 0
	v_mul_f32_e32 v28, v28, v166
	v_mul_f32_e32 v29, v29, v166
	v_mul_f32_e32 v30, v30, v166
	v_mul_f32_e32 v31, v31, v166
	v_pk_mul_f32 v[28:29], v[28:29], v[212:213]
	v_pk_mul_f32 v[30:31], v[30:31], v[214:215]
	v_mul_f32_e32 v24, v24, v166
	v_mul_f32_e32 v25, v25, v166
	v_mul_f32_e32 v26, v26, v166
	v_mul_f32_e32 v27, v27, v166
	v_pk_mul_f32 v[24:25], v[24:25], v[216:217]
	v_pk_mul_f32 v[26:27], v[26:27], v[218:219]
	v_mul_f32_e32 v16, v16, v166
	v_mul_f32_e32 v17, v17, v166
	v_mul_f32_e32 v18, v18, v166
	v_mul_f32_e32 v19, v19, v166
	v_pk_mul_f32 v[16:17], v[16:17], v[220:221]
	v_pk_mul_f32 v[18:19], v[18:19], v[222:223]
	v_mul_f32_e32 v8, v8, v166
	v_mul_f32_e32 v9, v9, v166
	v_mul_f32_e32 v10, v10, v166
	v_mul_f32_e32 v11, v11, v166
	v_pk_mul_f32 v[8:9], v[8:9], v[224:225]
	v_pk_mul_f32 v[10:11], v[10:11], v[226:227]
	global_store_dwordx4 v228, v[28:31], s[48:49] sc1 nt
	global_store_dwordx4 v228, v[24:27], s[48:49] offset:64 sc1 nt
	global_store_dwordx4 v228, v[16:19], s[48:49] offset:512 sc1 nt
	global_store_dwordx4 v228, v[8:11], s[48:49] offset:576 sc1 nt
	s_add_u32 s48, s42, 0xb0000
	s_addc_u32 s49, s43, 0
	v_mul_f32_e32 v20, v20, v167
	v_mul_f32_e32 v21, v21, v167
	v_mul_f32_e32 v22, v22, v167
	v_mul_f32_e32 v23, v23, v167
	v_pk_mul_f32 v[20:21], v[20:21], v[212:213]
	v_pk_mul_f32 v[22:23], v[22:23], v[214:215]
	v_mul_f32_e32 v12, v12, v167
	v_mul_f32_e32 v13, v13, v167
	v_mul_f32_e32 v14, v14, v167
	v_mul_f32_e32 v15, v15, v167
	v_pk_mul_f32 v[12:13], v[12:13], v[216:217]
	v_pk_mul_f32 v[14:15], v[14:15], v[218:219]
	v_mul_f32_e32 v4, v4, v167
	v_mul_f32_e32 v5, v5, v167
	v_mul_f32_e32 v6, v6, v167
	v_mul_f32_e32 v7, v7, v167
	v_pk_mul_f32 v[4:5], v[4:5], v[220:221]
	v_pk_mul_f32 v[6:7], v[6:7], v[222:223]
	v_mul_f32_e32 v0, v0, v167
	v_mul_f32_e32 v1, v1, v167
	v_mul_f32_e32 v2, v2, v167
	v_mul_f32_e32 v3, v3, v167
	v_pk_mul_f32 v[0:1], v[0:1], v[224:225]
	v_pk_mul_f32 v[2:3], v[2:3], v[226:227]
	global_store_dwordx4 v228, v[20:23], s[48:49] sc1 nt
	global_store_dwordx4 v228, v[12:15], s[48:49] offset:64 sc1 nt
	global_store_dwordx4 v228, v[4:7], s[48:49] offset:512 sc1 nt
	global_store_dwordx4 v228, v[0:3], s[48:49] offset:576 sc1 nt
